# weight conversion: the 8 per-row norm-gain (gk) values fetched with two scalar loads per item instead of 8 dependent global loads
# baseline (speedup 1.0000x reference)
.LBB0_466:
	s_abs_i32 s24, s51
	s_mul_hi_u32 s25, s24, s53
	s_mul_i32 s40, s25, s50
	s_sub_i32 s24, s24, s40
	s_ashr_i32 s22, s51, 31
	s_add_i32 s40, s25, 1
	s_sub_i32 s41, s24, s50
	s_cmp_ge_u32 s24, s50
	s_cselect_b32 s25, s40, s25
	s_cselect_b32 s24, s41, s24
	s_add_i32 s40, s25, 1
	s_cmp_ge_u32 s24, s50
	s_cselect_b32 s24, s40, s25
	v_readfirstlane_b32 s23, v204
	s_xor_b32 s24, s24, s22
	s_sub_i32 s24, s24, s22
	s_ashr_i32 s23, s23, 3
	s_lshl_b32 s22, s24, 6
	s_and_b32 s59, s23, -8
	s_mul_i32 s25, s56, s24
	s_mul_i32 s58, s52, s24
	s_add_i32 s24, s22, s59
	v_add_u32_e32 v2, s25, v41
	s_ashr_i32 s25, s24, 31
	s_mul_i32 s40, s25, s88
	s_mul_hi_u32 s41, s24, s88
	s_add_i32 s58, s58, s54
	s_add_i32 s41, s41, s40
	s_mul_i32 s40, s24, s88
	v_add_u32_e32 v3, s58, v42
	s_lshl_b64 s[40:41], s[40:41], 2
	v_cndmask_b32_e64 v2, v2, v3, s[2:3]
	s_add_u32 s40, s46, s40
	s_addc_u32 s41, s47, s41
	v_ashrrev_i32_e32 v3, 31, v2
	v_lshl_add_u64 v[2:3], v[2:3], 2, s[40:41]
	v_lshl_add_u64 v[4:5], s[88:89], 2, v[2:3]
	global_load_dwordx4 v[30:33], v[2:3], off
	global_load_dwordx4 v[26:29], v[4:5], off
	v_lshl_add_u64 v[2:3], v[4:5], 0, s[20:21]
	v_lshl_add_u64 v[4:5], v[2:3], 0, s[20:21]
	global_load_dwordx4 v[22:25], v[2:3], off
	global_load_dwordx4 v[18:21], v[4:5], off
	v_lshl_add_u64 v[2:3], v[4:5], 0, s[20:21]
	v_lshl_add_u64 v[4:5], v[2:3], 0, s[20:21]
	global_load_dwordx4 v[14:17], v[2:3], off
	global_load_dwordx4 v[10:13], v[4:5], off
	v_lshl_add_u64 v[2:3], v[4:5], 0, s[20:21]
	v_lshl_add_u64 v[4:5], v[2:3], 0, s[20:21]
	global_load_dwordx4 v[6:9], v[2:3], off
	s_nop 0
	global_load_dwordx4 v[2:5], v[4:5], off
	v_cndmask_b32_e64 v44, 0, 1, s[8:9]
	v_cmp_ne_u32_e64 s[40:41], 1, v44
	v_mov_b32_e32 v45, 1.0
	s_andn2_b64 vcc, exec, s[8:9]
	v_mov_b32_e32 v46, 1.0
	s_cbranch_vccnz .LBB0_468
	s_lshl_b64 s[60:61], s[24:25], 2
	s_add_u32 s60, s44, s60
	s_addc_u32 s61, s45, s61
	s_load_dwordx2 s[98:99], s[60:61], 0x0
	s_load_dwordx2 s[100:101], s[60:61], 0x8
	s_waitcnt lgkmcnt(0)
	v_mov_b32_e32 v46, s98
.LBB0_468:
	s_mulk_i32 s59, 0x214
	s_waitcnt vmcnt(0)
	v_mul_f32_e32 v30, v30, v46
	v_add_u32_e32 v44, s59, v38
	v_mul_f32_e32 v31, v31, v46
	v_cvt_pk_bf16_f32 v30, v30, v31
	ds_write_b32 v44, v30
	v_mul_f32_e32 v30, v32, v46
	s_and_b64 vcc, exec, s[40:41]
	v_mul_f32_e32 v31, v33, v46
	v_cvt_pk_bf16_f32 v30, v30, v31
	ds_write_b32 v44, v30 offset:4
	s_cbranch_vccnz .LBB0_470
	s_lshl_b64 s[60:61], s[24:25], 2
	s_add_u32 s60, s44, s60
	s_addc_u32 s61, s45, s61
	v_mov_b32_e32 v45, s99
.LBB0_470:
	s_waitcnt vmcnt(0)
	v_mul_f32_e32 v26, v26, v45
	v_mul_f32_e32 v27, v27, v45
	v_cvt_pk_bf16_f32 v26, v26, v27
	ds_write_b32 v44, v26 offset:532
	v_mul_f32_e32 v26, v28, v45
	v_mul_f32_e32 v27, v29, v45
	v_cvt_pk_bf16_f32 v26, v26, v27
	ds_write_b32 v44, v26 offset:536
	v_mov_b32_e32 v26, 1.0
	s_and_b64 vcc, exec, s[40:41]
	v_mov_b32_e32 v27, 1.0
	s_cbranch_vccnz .LBB0_472
	s_lshl_b64 s[60:61], s[24:25], 2
	s_add_u32 s60, s44, s60
	s_addc_u32 s61, s45, s61
	v_mov_b32_e32 v27, s100
.LBB0_472:
	s_waitcnt vmcnt(0)
	v_mul_f32_e32 v22, v22, v27
	v_mul_f32_e32 v23, v23, v27
	v_cvt_pk_bf16_f32 v22, v22, v23
	ds_write_b32 v44, v22 offset:1064
	v_mul_f32_e32 v22, v24, v27
	s_and_b64 vcc, exec, s[40:41]
	v_mul_f32_e32 v23, v25, v27
	v_cvt_pk_bf16_f32 v22, v22, v23
	ds_write_b32 v44, v22 offset:1068
	s_cbranch_vccnz .LBB0_474
	s_lshl_b64 s[60:61], s[24:25], 2
	s_add_u32 s60, s44, s60
	s_addc_u32 s61, s45, s61
	v_mov_b32_e32 v26, s101
.LBB0_474:
	s_waitcnt vmcnt(0)
	v_mul_f32_e32 v18, v18, v26
	v_mul_f32_e32 v19, v19, v26
	v_cvt_pk_bf16_f32 v18, v18, v19
	ds_write_b32 v44, v18 offset:1596
	v_mul_f32_e32 v18, v20, v26
	v_mul_f32_e32 v19, v21, v26
	v_cvt_pk_bf16_f32 v18, v18, v19
	ds_write_b32 v44, v18 offset:1600
	v_mov_b32_e32 v18, 1.0
	s_and_b64 vcc, exec, s[40:41]
	v_mov_b32_e32 v19, 1.0
	s_cbranch_vccnz .LBB0_476
	s_lshl_b64 s[60:61], s[24:25], 2
	s_add_u32 s60, s44, s60
	s_addc_u32 s61, s45, s61
	s_load_dwordx2 s[98:99], s[60:61], 0x10
	s_load_dwordx2 s[100:101], s[60:61], 0x18
	s_waitcnt lgkmcnt(0)
	v_mov_b32_e32 v19, s98
.LBB0_476:
	s_waitcnt vmcnt(0)
	v_mul_f32_e32 v14, v14, v19
	v_mul_f32_e32 v15, v15, v19
	v_cvt_pk_bf16_f32 v14, v14, v15
	ds_write_b32 v44, v14 offset:2128
	v_mul_f32_e32 v14, v16, v19
	s_and_b64 vcc, exec, s[40:41]
	v_mul_f32_e32 v15, v17, v19
	v_cvt_pk_bf16_f32 v14, v14, v15
	ds_write_b32 v44, v14 offset:2132
	s_cbranch_vccnz .LBB0_478
	s_lshl_b64 s[60:61], s[24:25], 2
	s_add_u32 s60, s44, s60
	s_addc_u32 s61, s45, s61
	v_mov_b32_e32 v18, s99
.LBB0_478:
	s_waitcnt vmcnt(0)
	v_mul_f32_e32 v10, v10, v18
	v_mul_f32_e32 v11, v11, v18
	v_cvt_pk_bf16_f32 v10, v10, v11
	ds_write_b32 v44, v10 offset:2660
	v_mul_f32_e32 v10, v12, v18
	v_mul_f32_e32 v11, v13, v18
	v_cvt_pk_bf16_f32 v10, v10, v11
	ds_write_b32 v44, v10 offset:2664
	v_mov_b32_e32 v10, 1.0
	s_and_b64 vcc, exec, s[40:41]
	v_mov_b32_e32 v11, 1.0
	s_cbranch_vccnz .LBB0_480
	s_lshl_b64 s[60:61], s[24:25], 2
	s_add_u32 s60, s44, s60
	s_addc_u32 s61, s45, s61
	v_mov_b32_e32 v11, s100
.LBB0_480:
	s_waitcnt vmcnt(0)
	v_mul_f32_e32 v6, v6, v11
	v_mul_f32_e32 v7, v7, v11
	v_cvt_pk_bf16_f32 v6, v6, v7
	ds_write_b32 v44, v6 offset:3192
	v_mul_f32_e32 v6, v8, v11
	s_and_b64 vcc, exec, s[40:41]
	v_mul_f32_e32 v7, v9, v11
	v_cvt_pk_bf16_f32 v6, v6, v7
	ds_write_b32 v44, v6 offset:3196
	s_cbranch_vccnz .LBB0_465
	s_lshl_b64 s[24:25], s[24:25], 2
	s_add_u32 s24, s44, s24
	s_addc_u32 s25, s45, s25
	v_mov_b32_e32 v10, s101
	s_branch .LBB0_465

.LBB0_558:
	s_abs_i32 s24, s52
	s_mul_hi_u32 s25, s24, s54
	s_mul_i32 s40, s25, s51
	s_sub_i32 s24, s24, s40
	s_ashr_i32 s22, s52, 31
	s_add_i32 s40, s25, 1
	s_sub_i32 s41, s24, s51
	s_cmp_ge_u32 s24, s51
	s_cselect_b32 s25, s40, s25
	s_cselect_b32 s24, s41, s24
	s_add_i32 s40, s25, 1
	s_cmp_ge_u32 s24, s51
	s_cselect_b32 s24, s40, s25
	v_readfirstlane_b32 s23, v204
	s_xor_b32 s24, s24, s22
	s_sub_i32 s24, s24, s22
	s_ashr_i32 s23, s23, 3
	s_lshl_b32 s22, s24, 6
	s_and_b32 s60, s23, -8
	s_mul_i32 s25, s57, s24
	s_mul_i32 s59, s53, s24
	s_add_i32 s24, s22, s60
	v_add_u32_e32 v2, s25, v41
	s_ashr_i32 s25, s24, 31
	s_mul_i32 s40, s25, s88
	s_mul_hi_u32 s41, s24, s88
	s_add_i32 s59, s59, s55
	s_add_i32 s41, s41, s40
	s_mul_i32 s40, s24, s88
	v_add_u32_e32 v3, s59, v42
	s_lshl_b64 s[40:41], s[40:41], 2
	v_cndmask_b32_e64 v2, v2, v3, s[2:3]
	s_add_u32 s40, s46, s40
	s_addc_u32 s41, s47, s41
	v_ashrrev_i32_e32 v3, 31, v2
	v_lshl_add_u64 v[2:3], v[2:3], 2, s[40:41]
	v_lshl_add_u64 v[4:5], s[88:89], 2, v[2:3]
	global_load_dwordx4 v[30:33], v[2:3], off
	global_load_dwordx4 v[26:29], v[4:5], off
	v_lshl_add_u64 v[2:3], v[4:5], 0, s[20:21]
	v_lshl_add_u64 v[4:5], v[2:3], 0, s[20:21]
	global_load_dwordx4 v[22:25], v[2:3], off
	global_load_dwordx4 v[18:21], v[4:5], off
	v_lshl_add_u64 v[2:3], v[4:5], 0, s[20:21]
	v_lshl_add_u64 v[4:5], v[2:3], 0, s[20:21]
	global_load_dwordx4 v[14:17], v[2:3], off
	global_load_dwordx4 v[10:13], v[4:5], off
	v_lshl_add_u64 v[2:3], v[4:5], 0, s[20:21]
	v_lshl_add_u64 v[4:5], v[2:3], 0, s[20:21]
	global_load_dwordx4 v[6:9], v[2:3], off
	s_nop 0
	global_load_dwordx4 v[2:5], v[4:5], off
	v_cndmask_b32_e64 v44, 0, 1, s[8:9]
	v_cmp_ne_u32_e64 s[40:41], 1, v44
	v_mov_b32_e32 v45, 1.0
	s_andn2_b64 vcc, exec, s[8:9]
	v_mov_b32_e32 v46, 1.0
	s_cbranch_vccnz .LBB0_560
	s_lshl_b64 s[62:63], s[24:25], 2
	s_add_u32 s62, s44, s62
	s_addc_u32 s63, s45, s63
	s_load_dwordx2 s[98:99], s[62:63], 0x0
	s_load_dwordx2 s[100:101], s[62:63], 0x8
	s_waitcnt lgkmcnt(0)
	v_mov_b32_e32 v46, s98
.LBB0_560:
	s_mulk_i32 s60, 0x214
	s_waitcnt vmcnt(0)
	v_mul_f32_e32 v30, v30, v46
	v_add_u32_e32 v44, s60, v38
	v_mul_f32_e32 v31, v31, v46
	v_cvt_pk_bf16_f32 v30, v30, v31
	ds_write_b32 v44, v30
	v_mul_f32_e32 v30, v32, v46
	s_and_b64 vcc, exec, s[40:41]
	v_mul_f32_e32 v31, v33, v46
	v_cvt_pk_bf16_f32 v30, v30, v31
	ds_write_b32 v44, v30 offset:4
	s_cbranch_vccnz .LBB0_562
	s_lshl_b64 s[60:61], s[24:25], 2
	s_add_u32 s60, s44, s60
	s_addc_u32 s61, s45, s61
	v_mov_b32_e32 v45, s99

.LBB0_621:
	s_abs_i32 s16, s36
	s_mul_hi_u32 s17, s16, s42
	s_mul_i32 s40, s17, s35
	s_sub_i32 s16, s16, s40
	s_ashr_i32 s14, s36, 31
	s_add_i32 s40, s17, 1
	s_sub_i32 s41, s16, s35
	s_cmp_ge_u32 s16, s35
	s_cselect_b32 s17, s40, s17
	s_cselect_b32 s16, s41, s16
	s_add_i32 s40, s17, 1
	s_cmp_ge_u32 s16, s35
	s_cselect_b32 s16, s40, s17
	v_readfirstlane_b32 s15, v204
	s_xor_b32 s16, s16, s14
	s_sub_i32 s16, s16, s14
	s_ashr_i32 s15, s15, 3
	s_lshl_b32 s14, s16, 6
	s_and_b32 s52, s15, -8
	s_mul_i32 s17, s49, s16
	s_mul_i32 s51, s37, s16
	s_add_i32 s16, s14, s52
	v_add_u32_e32 v2, s17, v42
	s_ashr_i32 s17, s16, 31
	s_mul_i32 s40, s17, s88
	s_mul_hi_u32 s41, s16, s88
	s_add_i32 s51, s51, s43
	s_add_i32 s41, s41, s40
	s_mul_i32 s40, s16, s88
	v_add_u32_e32 v3, s51, v43
	s_lshl_b64 s[40:41], s[40:41], 2
	v_cndmask_b32_e64 v2, v2, v3, s[2:3]
	s_add_u32 s40, s46, s40
	s_addc_u32 s41, s47, s41
	v_ashrrev_i32_e32 v3, 31, v2
	v_lshl_add_u64 v[2:3], v[2:3], 2, s[40:41]
	v_lshl_add_u64 v[4:5], s[88:89], 2, v[2:3]
	global_load_dwordx4 v[30:33], v[2:3], off
	global_load_dwordx4 v[26:29], v[4:5], off
	v_lshl_add_u64 v[2:3], v[4:5], 0, s[12:13]
	v_lshl_add_u64 v[4:5], v[2:3], 0, s[12:13]
	global_load_dwordx4 v[22:25], v[2:3], off
	global_load_dwordx4 v[18:21], v[4:5], off
	v_lshl_add_u64 v[2:3], v[4:5], 0, s[12:13]
	v_lshl_add_u64 v[4:5], v[2:3], 0, s[12:13]
	global_load_dwordx4 v[14:17], v[2:3], off
	global_load_dwordx4 v[10:13], v[4:5], off
	v_lshl_add_u64 v[2:3], v[4:5], 0, s[12:13]
	v_lshl_add_u64 v[4:5], v[2:3], 0, s[12:13]
	global_load_dwordx4 v[6:9], v[2:3], off
	s_nop 0
	global_load_dwordx4 v[2:5], v[4:5], off
	v_cndmask_b32_e64 v45, 0, 1, s[8:9]
	v_cmp_ne_u32_e64 s[40:41], 1, v45
	v_mov_b32_e32 v46, 1.0
	s_andn2_b64 vcc, exec, s[8:9]
	v_mov_b32_e32 v47, 1.0
	s_cbranch_vccnz .LBB0_623
	s_lshl_b64 s[54:55], s[16:17], 2
	s_add_u32 s54, s44, s54
	s_addc_u32 s55, s45, s55
	s_load_dwordx2 s[98:99], s[54:55], 0x0
	s_load_dwordx2 s[100:101], s[54:55], 0x8
	s_waitcnt lgkmcnt(0)
	v_mov_b32_e32 v47, s98
.LBB0_623:
	s_mulk_i32 s52, 0x214
	s_waitcnt vmcnt(0)
	v_mul_f32_e32 v30, v30, v47
	v_add_u32_e32 v45, s52, v39
	v_mul_f32_e32 v31, v31, v47
	v_cvt_pk_bf16_f32 v30, v30, v31
	ds_write_b32 v45, v30
	v_mul_f32_e32 v30, v32, v47
	s_and_b64 vcc, exec, s[40:41]
	v_mul_f32_e32 v31, v33, v47
	v_cvt_pk_bf16_f32 v30, v30, v31
	ds_write_b32 v45, v30 offset:4
	s_cbranch_vccnz .LBB0_625
	s_lshl_b64 s[52:53], s[16:17], 2
	s_add_u32 s52, s44, s52
	s_addc_u32 s53, s45, s53
	v_mov_b32_e32 v46, s99
.LBB0_625:
	s_waitcnt vmcnt(0)
	v_mul_f32_e32 v26, v26, v46
	v_mul_f32_e32 v27, v27, v46
	v_cvt_pk_bf16_f32 v26, v26, v27
	ds_write_b32 v45, v26 offset:532
	v_mul_f32_e32 v26, v28, v46
	v_mul_f32_e32 v27, v29, v46
	v_cvt_pk_bf16_f32 v26, v26, v27
	ds_write_b32 v45, v26 offset:536
	v_mov_b32_e32 v26, 1.0
	s_and_b64 vcc, exec, s[40:41]
	v_mov_b32_e32 v27, 1.0
	s_cbranch_vccnz .LBB0_627
	s_lshl_b64 s[52:53], s[16:17], 2
	s_add_u32 s52, s44, s52
	s_addc_u32 s53, s45, s53
	v_mov_b32_e32 v27, s100
.LBB0_627:
	s_waitcnt vmcnt(0)
	v_mul_f32_e32 v22, v22, v27
	v_mul_f32_e32 v23, v23, v27
	v_cvt_pk_bf16_f32 v22, v22, v23
	ds_write_b32 v45, v22 offset:1064
	v_mul_f32_e32 v22, v24, v27
	s_and_b64 vcc, exec, s[40:41]
	v_mul_f32_e32 v23, v25, v27
	v_cvt_pk_bf16_f32 v22, v22, v23
	ds_write_b32 v45, v22 offset:1068
	s_cbranch_vccnz .LBB0_629
	s_lshl_b64 s[52:53], s[16:17], 2
	s_add_u32 s52, s44, s52
	s_addc_u32 s53, s45, s53
	v_mov_b32_e32 v26, s101
.LBB0_629:
	s_waitcnt vmcnt(0)
	v_mul_f32_e32 v18, v18, v26
	v_mul_f32_e32 v19, v19, v26
	v_cvt_pk_bf16_f32 v18, v18, v19
	ds_write_b32 v45, v18 offset:1596
	v_mul_f32_e32 v18, v20, v26
	v_mul_f32_e32 v19, v21, v26
	v_cvt_pk_bf16_f32 v18, v18, v19
	ds_write_b32 v45, v18 offset:1600
	v_mov_b32_e32 v18, 1.0
	s_and_b64 vcc, exec, s[40:41]
	v_mov_b32_e32 v19, 1.0
	s_cbranch_vccnz .LBB0_631
	s_lshl_b64 s[52:53], s[16:17], 2
	s_add_u32 s52, s44, s52
	s_addc_u32 s53, s45, s53
	s_load_dwordx2 s[98:99], s[52:53], 0x10
	s_load_dwordx2 s[100:101], s[52:53], 0x18
	s_waitcnt lgkmcnt(0)
	v_mov_b32_e32 v19, s98
.LBB0_631:
	s_waitcnt vmcnt(0)
	v_mul_f32_e32 v14, v14, v19
	v_mul_f32_e32 v15, v15, v19
	v_cvt_pk_bf16_f32 v14, v14, v15
	ds_write_b32 v45, v14 offset:2128
	v_mul_f32_e32 v14, v16, v19
	s_and_b64 vcc, exec, s[40:41]
	v_mul_f32_e32 v15, v17, v19
	v_cvt_pk_bf16_f32 v14, v14, v15
	ds_write_b32 v45, v14 offset:2132
	s_cbranch_vccnz .LBB0_633
	s_lshl_b64 s[52:53], s[16:17], 2
	s_add_u32 s52, s44, s52
	s_addc_u32 s53, s45, s53
	v_mov_b32_e32 v18, s99
.LBB0_633:
	s_waitcnt vmcnt(0)
	v_mul_f32_e32 v10, v10, v18
	v_mul_f32_e32 v11, v11, v18
	v_cvt_pk_bf16_f32 v10, v10, v11
	ds_write_b32 v45, v10 offset:2660
	v_mul_f32_e32 v10, v12, v18
	v_mul_f32_e32 v11, v13, v18
	v_cvt_pk_bf16_f32 v10, v10, v11
	ds_write_b32 v45, v10 offset:2664
	v_mov_b32_e32 v10, 1.0
	s_and_b64 vcc, exec, s[40:41]
	v_mov_b32_e32 v11, 1.0
	s_cbranch_vccnz .LBB0_635
	s_lshl_b64 s[52:53], s[16:17], 2
	s_add_u32 s52, s44, s52
	s_addc_u32 s53, s45, s53
	v_mov_b32_e32 v11, s100
.LBB0_635:
	s_waitcnt vmcnt(0)
	v_mul_f32_e32 v6, v6, v11
	v_mul_f32_e32 v7, v7, v11
	v_cvt_pk_bf16_f32 v6, v6, v7
	ds_write_b32 v45, v6 offset:3192
	v_mul_f32_e32 v6, v8, v11
	s_and_b64 vcc, exec, s[40:41]
	v_mul_f32_e32 v7, v9, v11
	v_cvt_pk_bf16_f32 v6, v6, v7
	ds_write_b32 v45, v6 offset:3196
	s_cbranch_vccnz .LBB0_620
	s_lshl_b64 s[16:17], s[16:17], 2
	s_add_u32 s16, s44, s16
	s_addc_u32 s17, s45, s17
	v_mov_b32_e32 v10, s101
	s_branch .LBB0_620

	.amdhsa_kernel _Z4mega6Params
		.amdhsa_group_segment_fixed_size 0
		.amdhsa_private_segment_fixed_size 0
		.amdhsa_kernarg_size 520
		.amdhsa_user_sgpr_count 2
		.amdhsa_user_sgpr_dispatch_ptr 0
		.amdhsa_user_sgpr_queue_ptr 0
		.amdhsa_user_sgpr_kernarg_segment_ptr 1
		.amdhsa_user_sgpr_dispatch_id 0
		.amdhsa_user_sgpr_kernarg_preload_length 0
		.amdhsa_user_sgpr_kernarg_preload_offset 0
		.amdhsa_user_sgpr_private_segment_size 0
		.amdhsa_uses_dynamic_stack 0
		.amdhsa_enable_private_segment 0
		.amdhsa_system_sgpr_workgroup_id_x 1
		.amdhsa_system_sgpr_workgroup_id_y 0
		.amdhsa_system_sgpr_workgroup_id_z 0
		.amdhsa_system_sgpr_workgroup_info 0
		.amdhsa_system_vgpr_workitem_id 2
		.amdhsa_next_free_vgpr 255
		.amdhsa_next_free_sgpr 102
		.amdhsa_accum_offset 256
		.amdhsa_reserve_vcc 1
		.amdhsa_float_round_mode_32 0
		.amdhsa_float_round_mode_16_64 0
		.amdhsa_float_denorm_mode_32 3
		.amdhsa_float_denorm_mode_16_64 3
		.amdhsa_dx10_clamp 1
		.amdhsa_ieee_mode 1
		.amdhsa_fp16_overflow 0
		.amdhsa_tg_split 0
		.amdhsa_exception_fp_ieee_invalid_op 0
		.amdhsa_exception_fp_denorm_src 0
		.amdhsa_exception_fp_ieee_div_zero 0
		.amdhsa_exception_fp_ieee_overflow 0
		.amdhsa_exception_fp_ieee_underflow 0
		.amdhsa_exception_fp_ieee_inexact 0
		.amdhsa_exception_int_div_zero 0
	.end_amdhsa_kernel

amdhsa.kernels:
  - .agpr_count:     0
    .args:
      - .offset:         0
        .size:           264
        .value_kind:     by_value
      - .offset:         264
        .size:           4
        .value_kind:     hidden_block_count_x
      - .offset:         268
        .size:           4
        .value_kind:     hidden_block_count_y
      - .offset:         272
        .size:           4
        .value_kind:     hidden_block_count_z
      - .offset:         276
        .size:           2
        .value_kind:     hidden_group_size_x
      - .offset:         278
        .size:           2
        .value_kind:     hidden_group_size_y
      - .offset:         280
        .size:           2
        .value_kind:     hidden_group_size_z
      - .offset:         282
        .size:           2
        .value_kind:     hidden_remainder_x
      - .offset:         284
        .size:           2
        .value_kind:     hidden_remainder_y
      - .offset:         286
        .size:           2
        .value_kind:     hidden_remainder_z
      - .offset:         304
        .size:           8
        .value_kind:     hidden_global_offset_x
      - .offset:         312
        .size:           8
        .value_kind:     hidden_global_offset_y
      - .offset:         320
        .size:           8
        .value_kind:     hidden_global_offset_z
      - .offset:         328
        .size:           2
        .value_kind:     hidden_grid_dims
      - .offset:         352
        .size:           8
        .value_kind:     hidden_multigrid_sync_arg
      - .offset:         384
        .size:           4
        .value_kind:     hidden_dynamic_lds_size
    .group_segment_fixed_size: 0
    .kernarg_segment_align: 8
    .kernarg_segment_size: 520
    .language:       OpenCL C
    .language_version:
      - 2
      - 0
    .max_flat_workgroup_size: 512
    .name:           _Z4mega6Params
    .private_segment_fixed_size: 0
    .sgpr_count:     108
    .sgpr_spill_count: 55
    .symbol:         _Z4mega6Params.kd
    .uniform_work_group_size: 1
    .uses_dynamic_stack: false
    .vgpr_count:     255
    .vgpr_spill_count: 0
    .wavefront_size: 64
